# v28 plus rstd in the P4 fast path as fma + v_rsq_f32 without the denormal-range rescue sequence (argument >= 1e-6, bit-identical)
# speedup vs baseline: 1.0087x; 1.0087x over previous
;     __device__ __forceinline__ void operator()(f32x4 (&acc)[2][2][4][2], const Unit& u, int wr, int wc, int fr, int fq) const {
;     ...
;                     const float rs = rsqrtf(rss[tok] * (1.0f / 1024.0f) + EPSV);
; #pragma unroll
;                     for (int bj = 0; bj < 2; ++bj)
; #pragma unroll
;                         for (int n = 0; n < 2; ++n) acc[ai][bj][m][n] = acc[ai][bj][m][n] * rs;
.LBB0_568:
	s_mul_i32 s36, s12, 0xfe
	s_add_i32 s4, s36, -1
	s_movk_i32 s5, 0xf00
	s_cmp_lt_i32 s4, 0x10000
	s_cselect_b32 s5, s5, 0x1f00
	s_and_b32 s0, s4, s5
	s_cmp_lg_u32 s0, s5
	s_cselect_b64 s[0:1], -1, 0
	s_add_i32 s5, s12, 0xfffffdfc
	s_cmp_gt_u32 s5, 0xfffffdfc
	v_mov_b32_e32 v190, v237
	v_mov_b32_e32 v228, v236
	s_cselect_b64 s[6:7], -1, 0
	s_and_b64 s[12:13], s[6:7], s[0:1]
	v_add_u32_e32 v245, s48, v228
	v_add_u32_e32 v152, s4, v245
	s_mov_b64 s[0:1], -1
	s_and_b64 vcc, exec, s[12:13]
	s_mov_b32 s93, s17
	s_cbranch_vccz .LBB0_570
	v_ashrrev_i32_e32 v1, 31, v152
	v_mov_b32_e32 v0, v152
	v_lshl_add_u64 v[0:1], v[0:1], 2, s[60:61]
	s_waitcnt vmcnt(0)
	v_fmamk_f32 v0, v248, 0x3a800000, v242
	s_mov_b64 s[0:1], 0
	v_rsq_f32_e32 v4, v0
	s_nop 0
	v_pk_mul_f32 v[34:35], v[142:143], v[4:5] op_sel_hi:[1,0]
	v_pk_mul_f32 v[32:33], v[140:141], v[4:5] op_sel_hi:[1,0]
	v_pk_mul_f32 v[2:3], v[138:139], v[4:5] op_sel_hi:[1,0]
	v_pk_mul_f32 v[0:1], v[136:137], v[4:5] op_sel_hi:[1,0]
	v_pk_mul_f32 v[38:39], v[134:135], v[4:5] op_sel_hi:[1,0]
	v_pk_mul_f32 v[36:37], v[132:133], v[4:5] op_sel_hi:[1,0]
	v_pk_mul_f32 v[6:7], v[130:131], v[4:5] op_sel_hi:[1,0]
	v_pk_mul_f32 v[4:5], v[128:129], v[4:5] op_sel_hi:[1,0]
